# mix phase work queue: next work index fetched (atomic) at the start of the current item instead of between items
# speedup vs baseline: 1.0118x; 1.0012x over previous
; #define LAS __attribute__((address_space(3)))
; #define OPQV(x) asm volatile("" : "+v"(x))
; DEV void phase_mix(LAS unsigned char* lds, const bf16_t* P, const bf16_t* QB, const bf16_t* KV, const bf16_t* KC, const bf16_t* VC, const float* rel_bias, bf16_t* OB,
;                    const bf16_t* VN, const float* sgu_w, const float* sgu_b, bf16_t* OC, int* ctr) {
;     int tid = threadIdx.x; OPQV(tid);
;     LAS int* BK = (LAS int*)(lds + AT_BK);
;     if (tid < 129) { int bk; if (tid < 16) bk = tid; else { const float lr = log2f((float)tid * (1.f / 16.f)) * (1.f / 3.f); bk = 16 + (int)(lr * 16.f); if (bk > 31) bk = 31; } BK[tid] = bk; }
;     *(LAS float*)(lds + AT_RB + tid * 4) = rel_bias[tid];
;     __syncthreads();
.LBB0_156:
	s_or_b64 exec, exec, s[4:5]
	s_load_dwordx2 s[4:5], s[0:1], 0x8
	v_ashrrev_i32_e32 v3, 31, v2
	s_add_u32 s78, s62, 0x26988000
	s_addc_u32 s79, s63, 0
	s_add_u32 s70, s62, 0x20989000
	s_waitcnt lgkmcnt(0)
	v_lshl_add_u64 v[4:5], v[2:3], 2, s[4:5]
	global_load_dword v0, v[4:5], off
	s_addc_u32 s8, s63, 0
	s_ashr_i32 s15, s14, 31
	s_lshl_b64 s[4:5], s[14:15], 19
	s_add_u32 s80, s40, s4
	s_addc_u32 s81, s41, s5
	s_lshl_b64 s[4:5], s[14:15], 12
	s_add_u32 s82, s42, s4
	s_addc_u32 s83, s43, s5
	s_lshl_b32 s4, s14, 6
	s_ashr_i32 s5, s4, 31
	s_lshl_b64 s[4:5], s[4:5], 2
	s_add_u32 s4, s62, s4
	s_addc_u32 s5, s63, s5
	s_add_u32 s84, s4, 0x20988000
	s_addc_u32 s85, s5, 0
	s_add_u32 s86, s62, 0x1c988000
	s_addc_u32 s87, s63, 0
	v_lshl_add_u32 v3, v2, 2, 0
	s_add_u32 s88, s62, 0x1e988000
	v_add_u32_e32 v3, 0x13d00, v3
	s_addc_u32 s89, s63, 0
	v_cmp_eq_u32_e64 s[40:41], 0, v2
	s_waitcnt vmcnt(0)
	ds_write_b32 v3, v0
	s_waitcnt lgkmcnt(0)
	s_barrier
	s_mov_b32 s98, 0
	s_branch .LBB0_160

; #define LAS __attribute__((address_space(3)))
; #define OPQV(x) asm volatile("" : "+v"(x))
; DEV void sgu_item(LAS unsigned char* lds, const bf16_t* P, const bf16_t* VN, const float* sgu_w, const float* sgu_b, bf16_t* OC, int item) {
;     int tid = threadIdx.x; OPQV(tid); const int lane = tid & 63, wv = tid >> 6, fr = lane & 15, g4 = lane >> 4;
;     LAS bf16_t* VT = (LAS bf16_t*)lds;
;     const int g = item & 7, ch = (item >> 3) & 15, b = item >> 7;
;     const size_t tok0 = (size_t)b * S_ + ch * 128;
;     const int t = wv * 16 + fr;
;     const size_t tok = tok0 + t;
;     u32x4 vin[4];
; #pragma unroll
;     for (int it = 0; it < 4; ++it) { const int idx = it * 512 + tid, s = idx >> 4, c8 = (idx & 15) * 8; vin[it] = *(const u32x4*)(VN + (tok0 + s) * 1024 + g * 128 + c8); }
;     const float* wrow = sgu_w + ((size_t)g * 128 + t) * 128;
;     f32x4 wa[4], wb[4];
; #pragma unroll
;     for (int ks = 0; ks < 4; ++ks) { wa[ks] = *(const f32x4*)(wrow + ks * 32 + g4 * 8); wb[ks] = *(const f32x4*)(wrow + ks * 32 + g4 * 8 + 4); }
;     u32x2 uu[8];
; #pragma unroll
;     for (int n = 0; n < 8; ++n) uu[n] = *(const u32x2*)(P + tok * NP + COL_U + g * 128 + n * 16 + g4 * 4);
;     const float bias = sgu_b[g * 128 + t];
; #pragma unroll
;     for (int it = 0; it < 4; ++it) { const int idx = it * 512 + tid, s = idx >> 4, c8 = (idx & 15) * 8;
; #pragma unroll
;         for (int j = 0; j < 4; ++j) { VT[(c8 + 2 * j) * 136 + s] = (bf16_t)(vin[it][j] & 0xffffu); VT[(c8 + 2 * j + 1) * 136 + s] = (bf16_t)(vin[it][j] >> 16); } }
;     __syncthreads();
; DEV void phase_mix(LAS unsigned char* lds, const bf16_t* P, const bf16_t* QB, const bf16_t* KV, const bf16_t* KC, const bf16_t* VC, const float* rel_bias, bf16_t* OB,
;                    const bf16_t* VN, const float* sgu_w, const float* sgu_b, bf16_t* OC, int* ctr) {
;     ...
;     for (;;) {
;         if (tid == 0) *(LAS int*)(lds + AT_NEXT) = atomicAdd(ctr, 1);
;         __syncthreads();
;         const int i = *(const LAS int*)(lds + AT_NEXT);
;         __syncthreads();
;         if (i >= 2048) break;
;         if (i < 1024) attn_item(lds, P, QB, KV, KC, VC, rel_bias, OB, (i & 31) >> 2, i & 3, 31 - (i >> 5));
;         else sgu_item(lds, P, VN, sgu_w, sgu_b, OC, i - 1024);
.LBB0_160:
	s_and_saveexec_b64 s[4:5], s[40:41]
	s_cbranch_execz .LBB0_164
	s_cmp_eq_u32 s98, 0
	s_cbranch_scc0 .Lwq_have
	v_mov_b32_e32 v214, 1
	global_atomic_add v214, v1, v214, s[84:85] sc0
.Lwq_have:
	v_mov_b32_e32 v2, s95
	s_waitcnt vmcnt(0)
	ds_write_b32 v2, v214
.LBB0_164:
	s_or_b64 exec, exec, s[4:5]
	v_mov_b32_e32 v0, s95
	s_waitcnt lgkmcnt(0)
	s_barrier
	ds_read_b32 v0, v0
	s_movk_i32 s4, 0x7ff
	s_waitcnt lgkmcnt(0)
	s_barrier
	v_cmp_lt_i32_e32 vcc, s4, v0
	v_readfirstlane_b32 s43, v0
	s_mov_b64 s[4:5], -1
	s_cbranch_vccnz .LBB0_159
	s_mov_b32 s98, 1
	s_and_saveexec_b64 s[6:7], s[40:41]
	s_cbranch_execz .Lwq_skip
	v_mov_b32_e32 v214, 1
	global_atomic_add v214, v1, v214, s[84:85] sc0
.Lwq_skip:
	s_or_b64 exec, exec, s[6:7]
	s_cmpk_gt_i32 s43, 0x3ff
	s_cbranch_scc0 .LBB0_167
	s_add_i32 s4, s43, 0xfffffc00
	s_lshl_b32 s5, s4, 4
	s_lshl_b32 s4, s4, 7
	v_mov_b32_e32 v8, v210
	s_and_b32 s6, s4, 0x380
	s_and_b32 s36, s5, 0x3f80
	v_lshlrev_b32_e32 v0, 3, v8
	s_lshl_b32 s4, s6, 1
	v_and_b32_e32 v9, 0x78, v0
	s_add_u32 s44, s34, s4
	v_ashrrev_i32_e32 v4, 4, v8
	s_addc_u32 s45, s35, 0
	v_lshlrev_b32_e32 v0, 1, v9
	v_ashrrev_i32_e32 v5, 31, v4
	v_lshl_add_u64 v[2:3], s[44:45], 0, v[0:1]
	v_lshl_add_u64 v[6:7], v[4:5], 0, s[36:37]
	v_add_u32_e32 v0, 0x200, v8
	v_lshlrev_b64 v[6:7], 11, v[6:7]
	v_ashrrev_i32_e32 v70, 4, v0
	v_lshl_add_u64 v[6:7], v[2:3], 0, v[6:7]
	v_ashrrev_i32_e32 v71, 31, v70
	global_load_dwordx4 v[30:33], v[6:7], off
	v_lshl_add_u64 v[6:7], v[70:71], 0, s[36:37]
	v_add_u32_e32 v0, 0x400, v8
	v_lshlrev_b64 v[6:7], 11, v[6:7]
	v_ashrrev_i32_e32 v72, 4, v0
	v_lshl_add_u64 v[6:7], v[2:3], 0, v[6:7]
	v_ashrrev_i32_e32 v73, 31, v72
	global_load_dwordx4 v[34:37], v[6:7], off
	v_lshl_add_u64 v[6:7], v[72:73], 0, s[36:37]
	v_add_u32_e32 v0, 0x600, v8
	v_lshlrev_b64 v[6:7], 11, v[6:7]
	v_ashrrev_i32_e32 v74, 4, v0
	v_lshl_add_u64 v[6:7], v[2:3], 0, v[6:7]
	v_ashrrev_i32_e32 v75, 31, v74
	global_load_dwordx4 v[38:41], v[6:7], off
	v_lshl_add_u64 v[6:7], v[74:75], 0, s[36:37]
	v_ashrrev_i32_e32 v0, 2, v8
	v_lshlrev_b64 v[6:7], 11, v[6:7]
	s_waitcnt vmcnt(11)
	v_bfi_b32 v28, -16, v0, v8
	v_lshl_add_u64 v[2:3], v[2:3], 0, v[6:7]
	v_ashrrev_i32_e32 v29, 31, v28
	s_mov_b32 s7, s37
	global_load_dwordx4 v[42:45], v[2:3], off
	v_lshl_add_u64 v[2:3], v[28:29], 0, s[6:7]
	v_bfe_u32 v0, v8, 4, 2
	v_lshlrev_b64 v[2:3], 9, v[2:3]
	v_lshl_add_u64 v[2:3], s[80:81], 0, v[2:3]
	v_lshlrev_b32_e32 v6, 5, v0
	v_mov_b32_e32 v7, v1
	v_lshl_add_u64 v[6:7], v[2:3], 0, v[6:7]
	global_load_dwordx4 v[46:49], v[6:7], off
	global_load_dwordx4 v[50:53], v[6:7], off offset:16
	v_mov_b64_e32 v[2:3], s[76:77]
	v_and_b32_e32 v82, 15, v8
	v_add_u32_e32 v8, s6, v28
	s_movk_i32 s6, 0x110
	v_lshl_add_u64 v[24:25], v[28:29], 0, s[36:37]
	s_mov_b32 s5, s37
	v_mad_u32_u24 v71, v9, s6, 0
	v_ashrrev_i32_e32 v9, 31, v8
	v_mad_i64_i32 v[2:3], s[6:7], v24, s59, v[2:3]
	v_lshl_add_u32 v73, v4, 1, v71
	v_lshlrev_b32_e32 v0, 3, v0
	v_lshl_add_u64 v[4:5], v[8:9], 2, s[82:83]
	v_lshl_add_u64 v[2:3], v[2:3], 0, s[4:5]
	global_load_dword v29, v[4:5], off
	v_lshl_add_u64 v[10:11], v[2:3], 0, v[0:1]
	global_load_dwordx4 v[54:57], v[6:7], off offset:144
	global_load_dwordx4 v[58:61], v[6:7], off offset:128
	global_load_dwordx4 v[62:65], v[6:7], off offset:272
	global_load_dwordx4 v[66:69], v[6:7], off offset:256
	global_load_dwordx4 v[2:5], v[6:7], off offset:400
	s_nop 0
	global_load_dwordx4 v[6:9], v[6:7], off offset:384
	s_mov_b64 s[6:7], 0x2c00
	s_movk_i32 s5, 0x2000
	v_lshl_add_u64 v[76:77], v[10:11], 0, s[6:7]
	v_add_co_u32_e32 v10, vcc, s5, v10
	v_or_b32_e32 v90, 32, v0
	s_nop 0
	v_addc_co_u32_e32 v11, vcc, 0, v11, vcc
	global_load_dwordx2 v[22:23], v[76:77], off offset:32
	global_load_dwordx2 v[20:21], v[76:77], off offset:64
	global_load_dwordx2 v[18:19], v[76:77], off offset:96
	global_load_dwordx2 v[16:17], v[76:77], off offset:128
	global_load_dwordx2 v[26:27], v[10:11], off offset:3072
	global_load_dwordx2 v[14:15], v[76:77], off offset:160
	global_load_dwordx2 v[12:13], v[76:77], off offset:192
	s_nop 0
	global_load_dwordx2 v[10:11], v[76:77], off offset:224
	v_cmp_le_i32_e32 vcc, v0, v28
	v_or_b32_e32 v91, 33, v0
	s_movk_i32 s5, 0x88
	v_mad_u32_u24 v83, v82, s5, v227
	v_mad_u32_u24 v84, v82, s5, v252
	v_mad_u32_u24 v85, v82, s5, v216
	v_mad_u32_u24 v86, v82, s5, v217
	v_mad_u32_u24 v87, v82, s5, v218
	s_waitcnt vmcnt(20)
	ds_write_b16 v73, v30
	ds_write_b16_d16_hi v73, v30 offset:272
	ds_write_b16 v73, v31 offset:544
	ds_write_b16_d16_hi v73, v31 offset:816
	ds_write_b16 v73, v32 offset:1088
	ds_write_b16_d16_hi v73, v32 offset:1360
	ds_write_b16 v73, v33 offset:1632
	ds_write_b16_d16_hi v73, v33 offset:1904
	v_lshl_add_u32 v30, v70, 1, v71
	s_waitcnt vmcnt(19)
	ds_write_b16 v30, v34
	ds_write_b16_d16_hi v30, v34 offset:272
	ds_write_b16 v30, v35 offset:544
	ds_write_b16_d16_hi v30, v35 offset:816
	ds_write_b16 v30, v36 offset:1088
	ds_write_b16_d16_hi v30, v36 offset:1360
	ds_write_b16 v30, v37 offset:1632
	ds_write_b16_d16_hi v30, v37 offset:1904
	v_lshl_add_u32 v30, v72, 1, v71
	s_waitcnt vmcnt(18)
	ds_write_b16 v30, v38
	ds_write_b16_d16_hi v30, v38 offset:272
	ds_write_b16 v30, v39 offset:544
	ds_write_b16_d16_hi v30, v39 offset:816
	ds_write_b16 v30, v40 offset:1088
	ds_write_b16_d16_hi v30, v40 offset:1360
	ds_write_b16 v30, v41 offset:1632
	ds_write_b16_d16_hi v30, v41 offset:1904
	v_lshl_add_u32 v30, v74, 1, v71
	s_waitcnt vmcnt(17)
	ds_write_b16 v30, v42
	ds_write_b16_d16_hi v30, v42 offset:272
	ds_write_b16 v30, v43 offset:544
	ds_write_b16_d16_hi v30, v43 offset:816
	ds_write_b16 v30, v44 offset:1088
	ds_write_b16_d16_hi v30, v44 offset:1360
	ds_write_b16 v30, v45 offset:1632
	ds_write_b16_d16_hi v30, v45 offset:1904
	v_or_b32_e32 v32, 2, v0
	v_or_b32_e32 v33, 3, v0
	v_or_b32_e32 v34, 4, v0
	v_or_b32_e32 v35, 5, v0
	v_or_b32_e32 v36, 6, v0
	v_or_b32_e32 v37, 7, v0
	s_waitcnt vmcnt(16) lgkmcnt(0)
	v_cndmask_b32_e32 v30, 0, v46, vcc
	v_cmp_lt_i32_e32 vcc, v0, v28
	s_barrier
; #define LAS __attribute__((address_space(3)))
; DEV u32x4 pack8(const float (&f)[8]) { u32x4 w; w.x = cvt_pk_bf16(f[0], f[1]); w.y = cvt_pk_bf16(f[2], f[3]); w.z = cvt_pk_bf16(f[4], f[5]); w.w = cvt_pk_bf16(f[6], f[7]); return w; }
; DEV void sgu_item(LAS unsigned char* lds, const bf16_t* P, const bf16_t* VN, const float* sgu_w, const float* sgu_b, bf16_t* OC, int item) {
;     ...
;     f32x4 acc[8];
; #pragma unroll
;     for (int n = 0; n < 8; ++n) acc[n] = (f32x4){0.f, 0.f, 0.f, 0.f};
; #pragma unroll
;     for (int ks = 0; ks < 4; ++ks) { const int s0 = ks * 32 + g4 * 8;
;         float wf[8] = {wa[ks][0], wa[ks][1], wa[ks][2], wa[ks][3], wb[ks][0], wb[ks][1], wb[ks][2], wb[ks][3]};
; #pragma unroll
;         for (int j = 0; j < 8; ++j) if (s0 + j > t) wf[j] = 0.f;
;         const bf16x8 wfr = as_bf16x8(pack8(wf));
; #pragma unroll
;         for (int n = 0; n < 8; ++n) { const bf16x8 vf = *(const LAS bf16x8*)(lds + ((n * 16 + fr) * 136 + s0) * 2);
;             acc[n] = __builtin_amdgcn_mfma_f32_16x16x32_bf16(vf, wfr, acc[n], 0, 0, 0); } }
	s_nop 0
	v_cndmask_b32_e32 v31, 0, v47, vcc
	v_cmp_le_i32_e32 vcc, v32, v28
	v_cvt_pk_bf16_f32 v30, v30, v31
	v_mad_u32_u24 v88, v82, s5, v219
	v_mad_u32_u24 v89, v82, s5, v220
	v_cndmask_b32_e32 v32, 0, v48, vcc
	v_cmp_le_i32_e32 vcc, v33, v28
	v_add_u32_e32 v38, v83, v0
	v_add_u32_e32 v42, v84, v0
	v_cndmask_b32_e32 v33, 0, v49, vcc
	v_cmp_le_i32_e32 vcc, v34, v28
	v_cvt_pk_bf16_f32 v31, v32, v33
	v_add_u32_e32 v46, v85, v0
	v_add_u32_e32 v70, v87, v0
	s_waitcnt vmcnt(15)
	v_cndmask_b32_e32 v34, 0, v50, vcc
	v_cmp_le_i32_e32 vcc, v35, v28
	v_add_u32_e32 v50, v86, v0
	v_add_u32_e32 v74, v88, v0
	v_cndmask_b32_e32 v35, 0, v51, vcc
	v_cmp_le_i32_e32 vcc, v36, v28
	v_cvt_pk_bf16_f32 v32, v34, v35
	v_mad_u32_u24 v34, v82, s5, v0
	v_lshl_add_u32 v34, v34, 1, 0
	v_cndmask_b32_e32 v36, 0, v52, vcc
	v_cmp_le_i32_e32 vcc, v37, v28
	v_add_u32_e32 v78, v89, v0
	v_lshl_add_u32 v38, v38, 1, 0
	v_cndmask_b32_e32 v37, 0, v53, vcc
	v_cmp_le_i32_e32 vcc, v90, v28
	v_cvt_pk_bf16_f32 v33, v36, v37
	ds_read_b128 v[34:37], v34
	ds_read_b128 v[38:41], v38
	s_waitcnt vmcnt(12)
	v_cndmask_b32_e32 v58, 0, v58, vcc
	v_cmp_le_i32_e32 vcc, v91, v28
	v_or_b32_e32 v91, 34, v0
	v_lshl_add_u32 v42, v42, 1, 0
	v_cndmask_b32_e32 v59, 0, v59, vcc
	v_cmp_le_i32_e32 vcc, v91, v28
	v_or_b32_e32 v91, 35, v0
	v_lshl_add_u32 v46, v46, 1, 0
	v_cndmask_b32_e32 v60, 0, v60, vcc
	v_cmp_le_i32_e32 vcc, v91, v28
	v_or_b32_e32 v91, 36, v0
	v_lshl_add_u32 v50, v50, 1, 0
	v_cndmask_b32_e32 v61, 0, v61, vcc
	v_cmp_le_i32_e32 vcc, v91, v28
	v_lshl_add_u32 v70, v70, 1, 0
	v_lshl_add_u32 v74, v74, 1, 0
	v_cndmask_b32_e32 v91, 0, v54, vcc
	v_or_b32_e32 v54, 37, v0
	v_cmp_le_i32_e32 vcc, v54, v28
	v_or_b32_e32 v54, 38, v0
	v_lshl_add_u32 v78, v78, 1, 0
	v_cndmask_b32_e32 v92, 0, v55, vcc
	v_cmp_le_i32_e32 vcc, v54, v28
	v_or_b32_e32 v54, 39, v0
	ds_read_b128 v[42:45], v42
	ds_read_b128 v[46:49], v46
	ds_read_b128 v[50:53], v50
	ds_read_b128 v[70:73], v70
	ds_read_b128 v[74:77], v74
	ds_read_b128 v[78:81], v78
	v_cndmask_b32_e32 v93, 0, v56, vcc
	v_cmp_le_i32_e32 vcc, v54, v28
	v_cvt_pk_bf16_f32 v54, v58, v59
	v_mad_u32_u24 v58, v82, s5, v90
	v_lshl_add_u32 v58, v58, 1, 0
	v_cndmask_b32_e32 v57, 0, v57, vcc
	v_cvt_pk_bf16_f32 v55, v60, v61
	v_cvt_pk_bf16_f32 v56, v91, v92
	v_cvt_pk_bf16_f32 v57, v93, v57
	ds_read_b128 v[58:61], v58
	s_waitcnt lgkmcnt(8)
	v_mfma_f32_16x16x32_bf16 v[34:37], v[34:37], v[30:33], 0
	v_lshlrev_b64 v[24:25], 11, v[24:25]
	v_lshl_add_u64 v[24:25], s[88:89], 0, v[24:25]
	s_waitcnt lgkmcnt(7)
	v_mfma_f32_16x16x32_bf16 v[38:41], v[38:41], v[30:33], 0
	s_waitcnt lgkmcnt(6)
	v_mfma_f32_16x16x32_bf16 v[42:45], v[42:45], v[30:33], 0
	s_waitcnt lgkmcnt(5)
	v_mfma_f32_16x16x32_bf16 v[46:49], v[46:49], v[30:33], 0
	s_waitcnt lgkmcnt(4)
	v_mfma_f32_16x16x32_bf16 v[50:53], v[50:53], v[30:33], 0
	s_waitcnt lgkmcnt(3)
	v_mfma_f32_16x16x32_bf16 v[70:73], v[70:73], v[30:33], 0
	s_waitcnt lgkmcnt(2)
	v_mfma_f32_16x16x32_bf16 v[74:77], v[74:77], v[30:33], 0
	s_waitcnt lgkmcnt(1)
	v_mfma_f32_16x16x32_bf16 v[30:33], v[78:81], v[30:33], 0
	v_add_u32_e32 v78, v90, v83
	v_lshl_add_u32 v78, v78, 1, 0
	ds_read_b128 v[78:81], v78
	s_waitcnt lgkmcnt(1)
	v_mfma_f32_16x16x32_bf16 v[34:37], v[58:61], v[54:57], v[34:37]
	v_add_u32_e32 v58, v90, v84
	v_lshl_add_u32 v58, v58, 1, 0
	ds_read_b128 v[58:61], v58
	s_waitcnt lgkmcnt(1)
	v_mfma_f32_16x16x32_bf16 v[38:41], v[78:81], v[54:57], v[38:41]
	v_add_u32_e32 v78, v90, v85
	v_lshl_add_u32 v78, v78, 1, 0
	ds_read_b128 v[78:81], v78
	s_waitcnt lgkmcnt(1)
	v_mfma_f32_16x16x32_bf16 v[42:45], v[58:61], v[54:57], v[42:45]
	v_add_u32_e32 v58, v90, v86
	v_lshl_add_u32 v58, v58, 1, 0
	ds_read_b128 v[58:61], v58
	s_waitcnt lgkmcnt(1)
	v_mfma_f32_16x16x32_bf16 v[46:49], v[78:81], v[54:57], v[46:49]
	v_add_u32_e32 v78, v90, v87
	v_lshl_add_u32 v78, v78, 1, 0
	ds_read_b128 v[78:81], v78
	s_waitcnt lgkmcnt(1)
	v_mfma_f32_16x16x32_bf16 v[50:53], v[58:61], v[54:57], v[50:53]
	v_add_u32_e32 v58, v90, v88
	v_lshl_add_u32 v58, v58, 1, 0
	ds_read_b128 v[58:61], v58
	s_waitcnt lgkmcnt(1)
	v_mfma_f32_16x16x32_bf16 v[70:73], v[78:81], v[54:57], v[70:73]
	v_add_u32_e32 v78, v90, v89
	v_lshl_add_u32 v78, v78, 1, 0
	ds_read_b128 v[78:81], v78
	s_waitcnt lgkmcnt(1)
	v_mfma_f32_16x16x32_bf16 v[58:61], v[58:61], v[54:57], v[74:77]
	s_nop 2
	v_or_b32_e32 v74, 64, v0
	v_cmp_le_i32_e32 vcc, v74, v28
	v_or_b32_e32 v75, 0x41, v0
	s_waitcnt lgkmcnt(0)
	v_mfma_f32_16x16x32_bf16 v[30:33], v[78:81], v[54:57], v[30:33]
	s_waitcnt vmcnt(10)
	v_cndmask_b32_e32 v66, 0, v66, vcc
	v_cmp_le_i32_e32 vcc, v75, v28
	v_or_b32_e32 v75, 0x42, v0
	v_add_u32_e32 v54, v74, v83
	v_cndmask_b32_e32 v67, 0, v67, vcc
	v_cmp_le_i32_e32 vcc, v75, v28
	v_or_b32_e32 v75, 0x43, v0
	v_lshl_add_u32 v54, v54, 1, 0
	v_cndmask_b32_e32 v68, 0, v68, vcc
	v_cmp_le_i32_e32 vcc, v75, v28
	v_or_b32_e32 v75, 0x44, v0
	s_nop 0
	v_cndmask_b32_e32 v69, 0, v69, vcc
	v_cmp_le_i32_e32 vcc, v75, v28
	s_nop 1
	v_cndmask_b32_e32 v75, 0, v62, vcc
	v_or_b32_e32 v62, 0x45, v0
	v_cmp_le_i32_e32 vcc, v62, v28
	v_or_b32_e32 v62, 0x46, v0
	s_nop 0
	v_cndmask_b32_e32 v76, 0, v63, vcc
	v_cmp_le_i32_e32 vcc, v62, v28
	v_or_b32_e32 v62, 0x47, v0
	s_nop 0
	v_cndmask_b32_e32 v77, 0, v64, vcc
	v_cmp_le_i32_e32 vcc, v62, v28
	v_cvt_pk_bf16_f32 v62, v66, v67
	v_mad_u32_u24 v66, v82, s5, v74
	v_lshl_add_u32 v66, v66, 1, 0
	v_cndmask_b32_e32 v65, 0, v65, vcc
	v_cvt_pk_bf16_f32 v63, v68, v69
	v_cvt_pk_bf16_f32 v64, v75, v76
	v_cvt_pk_bf16_f32 v65, v77, v65
	ds_read_b128 v[66:69], v66
	ds_read_b128 v[54:57], v54
	s_waitcnt lgkmcnt(1)
	v_mfma_f32_16x16x32_bf16 v[34:37], v[66:69], v[62:65], v[34:37]
	v_add_u32_e32 v66, v74, v84
	v_lshl_add_u32 v66, v66, 1, 0
	ds_read_b128 v[66:69], v66
	s_waitcnt lgkmcnt(1)
; #define LAS __attribute__((address_space(3)))
; DEV float bflo(unsigned u) { return __uint_as_float(u << 16); }
; DEV float bfhi(unsigned u) { return __uint_as_float(u & 0xffff0000u); }
; DEV unsigned cvt_pk_bf16(float lo, float hi) { unsigned r; asm volatile("v_cvt_pk_bf16_f32 %0, %1, %2" : "=v"(r) : "v"(lo), "v"(hi)); return r; }
; DEV u32x4 pack8(const float (&f)[8]) { u32x4 w; w.x = cvt_pk_bf16(f[0], f[1]); w.y = cvt_pk_bf16(f[2], f[3]); w.z = cvt_pk_bf16(f[4], f[5]); w.w = cvt_pk_bf16(f[6], f[7]); return w; }
; DEV void sgu_item(LAS unsigned char* lds, const bf16_t* P, const bf16_t* VN, const float* sgu_w, const float* sgu_b, bf16_t* OC, int item) {
;     ...
; #pragma unroll
;     for (int ks = 0; ks < 4; ++ks) { const int s0 = ks * 32 + g4 * 8;
;         float wf[8] = {wa[ks][0], wa[ks][1], wa[ks][2], wa[ks][3], wb[ks][0], wb[ks][1], wb[ks][2], wb[ks][3]};
; #pragma unroll
;         for (int j = 0; j < 8; ++j) if (s0 + j > t) wf[j] = 0.f;
;         const bf16x8 wfr = as_bf16x8(pack8(wf));
; #pragma unroll
;         for (int n = 0; n < 8; ++n) { const bf16x8 vf = *(const LAS bf16x8*)(lds + ((n * 16 + fr) * 136 + s0) * 2);
;             acc[n] = __builtin_amdgcn_mfma_f32_16x16x32_bf16(vf, wfr, acc[n], 0, 0, 0); } }
; #pragma unroll
;     for (int n = 0; n < 8; ++n) { const int c = g * 128 + n * 16 + g4 * 4;
;         u32x2 w; w.x = cvt_pk_bf16(bflo(uu[n].x) * (acc[n][0] + bias), bfhi(uu[n].x) * (acc[n][1] + bias)); w.y = cvt_pk_bf16(bflo(uu[n].y) * (acc[n][2] + bias), bfhi(uu[n].y) * (acc[n][3] + bias));
	v_mfma_f32_16x16x32_bf16 v[38:41], v[54:57], v[62:65], v[38:41]
	v_add_u32_e32 v54, v74, v85
	v_lshl_add_u32 v54, v54, 1, 0
	ds_read_b128 v[54:57], v54
	s_waitcnt lgkmcnt(1)
	v_mfma_f32_16x16x32_bf16 v[42:45], v[66:69], v[62:65], v[42:45]
	v_add_u32_e32 v66, v74, v86
	v_lshl_add_u32 v66, v66, 1, 0
	ds_read_b128 v[66:69], v66
	s_waitcnt lgkmcnt(1)
	v_mfma_f32_16x16x32_bf16 v[46:49], v[54:57], v[62:65], v[46:49]
	v_add_u32_e32 v54, v74, v87
	v_lshl_add_u32 v54, v54, 1, 0
	ds_read_b128 v[54:57], v54
	s_waitcnt lgkmcnt(1)
	v_mfma_f32_16x16x32_bf16 v[50:53], v[66:69], v[62:65], v[50:53]
	v_add_u32_e32 v66, v74, v88
	v_lshl_add_u32 v66, v66, 1, 0
	ds_read_b128 v[66:69], v66
	s_waitcnt lgkmcnt(1)
	v_mfma_f32_16x16x32_bf16 v[54:57], v[54:57], v[62:65], v[70:73]
	s_nop 2
	v_add_u32_e32 v70, v74, v89
	v_lshl_add_u32 v70, v70, 1, 0
	ds_read_b128 v[70:73], v70
	s_waitcnt lgkmcnt(1)
	v_mfma_f32_16x16x32_bf16 v[58:61], v[66:69], v[62:65], v[58:61]
	v_or_b32_e32 v66, 0x60, v0
	v_cmp_le_i32_e32 vcc, v66, v28
	v_or_b32_e32 v67, 0x61, v0
	s_waitcnt lgkmcnt(0)
	v_mfma_f32_16x16x32_bf16 v[30:33], v[70:73], v[62:65], v[30:33]
	s_waitcnt vmcnt(8)
	v_cndmask_b32_e32 v6, 0, v6, vcc
	v_cmp_le_i32_e32 vcc, v67, v28
	v_or_b32_e32 v67, 0x62, v0
	s_nop 0
	v_cndmask_b32_e32 v7, 0, v7, vcc
	v_cmp_le_i32_e32 vcc, v67, v28
	v_or_b32_e32 v67, 0x63, v0
	s_nop 0
	v_cndmask_b32_e32 v8, 0, v8, vcc
	v_cmp_le_i32_e32 vcc, v67, v28
	v_or_b32_e32 v67, 0x64, v0
	s_nop 0
	v_cndmask_b32_e32 v9, 0, v9, vcc
	v_cmp_le_i32_e32 vcc, v67, v28
	s_nop 1
	v_cndmask_b32_e32 v67, 0, v2, vcc
	v_or_b32_e32 v2, 0x65, v0
	v_cmp_le_i32_e32 vcc, v2, v28
	v_or_b32_e32 v2, 0x66, v0
	s_nop 0
	v_cndmask_b32_e32 v68, 0, v3, vcc
	v_cmp_le_i32_e32 vcc, v2, v28
	v_or_b32_e32 v2, 0x67, v0
	v_or_b32_e32 v0, s4, v0
	v_cndmask_b32_e32 v69, 0, v4, vcc
	v_cmp_le_i32_e32 vcc, v2, v28
	v_cvt_pk_bf16_f32 v2, v6, v7
	v_mad_u32_u24 v6, v82, s5, v66
	v_lshl_add_u32 v6, v6, 1, 0
	v_cndmask_b32_e32 v5, 0, v5, vcc
	v_cvt_pk_bf16_f32 v3, v8, v9
	v_cvt_pk_bf16_f32 v4, v67, v68
	v_cvt_pk_bf16_f32 v5, v69, v5
	ds_read_b128 v[6:9], v6
	v_add_u32_e32 v28, v66, v83
	v_lshl_add_u32 v28, v28, 1, 0
	ds_read_b128 v[62:65], v28
	v_add_u32_e32 v28, v66, v84
	v_lshl_add_u32 v28, v28, 1, 0
	s_waitcnt lgkmcnt(1)
	v_mfma_f32_16x16x32_bf16 v[6:9], v[6:9], v[2:5], v[34:37]
	s_nop 2
	ds_read_b128 v[34:37], v28
	v_add_u32_e32 v28, v66, v85
	v_lshl_add_u32 v28, v28, 1, 0
	s_waitcnt lgkmcnt(1)
	v_mfma_f32_16x16x32_bf16 v[38:41], v[62:65], v[2:5], v[38:41]
	ds_read_b128 v[62:65], v28
	v_add_u32_e32 v28, v66, v86
	v_lshl_add_u32 v28, v28, 1, 0
	s_waitcnt lgkmcnt(1)
	v_mfma_f32_16x16x32_bf16 v[34:37], v[34:37], v[2:5], v[42:45]
	v_add_f32_e32 v6, v29, v6
	s_nop 1
	ds_read_b128 v[42:45], v28
	v_add_u32_e32 v28, v66, v87
	v_lshl_add_u32 v28, v28, 1, 0
	s_waitcnt lgkmcnt(1)
	v_mfma_f32_16x16x32_bf16 v[46:49], v[62:65], v[2:5], v[46:49]
	ds_read_b128 v[62:65], v28
	v_add_u32_e32 v28, v66, v88
	v_lshl_add_u32 v28, v28, 1, 0
	s_waitcnt lgkmcnt(1)
	v_mfma_f32_16x16x32_bf16 v[42:45], v[42:45], v[2:5], v[50:53]
	v_add_f32_e32 v7, v29, v7
	s_nop 1
	ds_read_b128 v[50:53], v28
	v_add_u32_e32 v28, v66, v89
	v_lshl_add_u32 v28, v28, 1, 0
	s_waitcnt lgkmcnt(1)
	v_mfma_f32_16x16x32_bf16 v[54:57], v[62:65], v[2:5], v[54:57]
	ds_read_b128 v[62:65], v28
	s_waitcnt vmcnt(3)
; DEV float bflo(unsigned u) { return __uint_as_float(u << 16); }
; DEV float bfhi(unsigned u) { return __uint_as_float(u & 0xffff0000u); }
; DEV unsigned cvt_pk_bf16(float lo, float hi) { unsigned r; asm volatile("v_cvt_pk_bf16_f32 %0, %1, %2" : "=v"(r) : "v"(lo), "v"(hi)); return r; }
; DEV void sgu_item(LAS unsigned char* lds, const bf16_t* P, const bf16_t* VN, const float* sgu_w, const float* sgu_b, bf16_t* OC, int item) {
;     ...
; #pragma unroll
;     for (int n = 0; n < 8; ++n) { const int c = g * 128 + n * 16 + g4 * 4;
;         u32x2 w; w.x = cvt_pk_bf16(bflo(uu[n].x) * (acc[n][0] + bias), bfhi(uu[n].x) * (acc[n][1] + bias)); w.y = cvt_pk_bf16(bflo(uu[n].y) * (acc[n][2] + bias), bfhi(uu[n].y) * (acc[n][3] + bias));
;         *(u32x2*)(OC + tok * 1024 + c) = w; }
;     __syncthreads();
	v_lshlrev_b32_e32 v28, 16, v26
	v_and_b32_e32 v26, 0xffff0000, v26
	v_mul_f32_e32 v6, v6, v28
	v_mul_f32_e32 v7, v7, v26
	v_cvt_pk_bf16_f32 v6, v6, v7
	v_lshlrev_b32_e32 v7, 16, v27
	v_add_f32_e32 v8, v29, v8
	v_mul_f32_e32 v7, v8, v7
	v_and_b32_e32 v8, 0xffff0000, v27
	v_add_f32_e32 v9, v29, v9
	v_mul_f32_e32 v8, v9, v8
	v_cvt_pk_bf16_f32 v7, v7, v8
	v_lshl_add_u64 v[8:9], v[24:25], 0, v[0:1]
	global_store_dwordx2 v[8:9], v[6:7], off
	v_lshlrev_b32_e32 v0, 16, v22
	v_add_f32_e32 v6, v29, v38
	v_mul_f32_e32 v0, v6, v0
	v_and_b32_e32 v6, 0xffff0000, v22
	v_add_f32_e32 v7, v29, v39
	v_mul_f32_e32 v6, v7, v6
	v_cvt_pk_bf16_f32 v6, v0, v6
	v_lshlrev_b32_e32 v0, 16, v23
	v_add_f32_e32 v7, v29, v40
	v_mul_f32_e32 v0, v7, v0
	v_and_b32_e32 v7, 0xffff0000, v23
	v_add_f32_e32 v22, v29, v41
	v_mul_f32_e32 v7, v22, v7
	v_cvt_pk_bf16_f32 v7, v0, v7
	global_store_dwordx2 v[8:9], v[6:7], off offset:32
	v_lshlrev_b32_e32 v0, 16, v20
	v_add_f32_e32 v6, v29, v34
	v_mul_f32_e32 v0, v6, v0
	v_and_b32_e32 v6, 0xffff0000, v20
	v_add_f32_e32 v7, v29, v35
	v_mul_f32_e32 v6, v7, v6
	v_cvt_pk_bf16_f32 v6, v0, v6
	v_lshlrev_b32_e32 v0, 16, v21
	v_add_f32_e32 v7, v29, v36
	v_mul_f32_e32 v0, v7, v0
	v_and_b32_e32 v7, 0xffff0000, v21
	v_add_f32_e32 v20, v29, v37
	v_mul_f32_e32 v7, v20, v7
	v_cvt_pk_bf16_f32 v7, v0, v7
	global_store_dwordx2 v[8:9], v[6:7], off offset:64
	v_lshlrev_b32_e32 v0, 16, v18
	v_add_f32_e32 v6, v29, v46
	v_mul_f32_e32 v0, v6, v0
	v_and_b32_e32 v6, 0xffff0000, v18
	v_add_f32_e32 v7, v29, v47
	v_mul_f32_e32 v6, v7, v6
	v_cvt_pk_bf16_f32 v6, v0, v6
	v_lshlrev_b32_e32 v0, 16, v19
	v_add_f32_e32 v7, v29, v48
	v_mul_f32_e32 v0, v7, v0
	v_and_b32_e32 v7, 0xffff0000, v19
	v_add_f32_e32 v18, v29, v49
	v_mul_f32_e32 v7, v18, v7
	v_cvt_pk_bf16_f32 v7, v0, v7
	global_store_dwordx2 v[8:9], v[6:7], off offset:96
	v_lshlrev_b32_e32 v0, 16, v16
	v_add_f32_e32 v6, v29, v42
	v_mul_f32_e32 v0, v6, v0
	v_and_b32_e32 v6, 0xffff0000, v16
	v_add_f32_e32 v7, v29, v43
	v_mul_f32_e32 v6, v7, v6
	v_cvt_pk_bf16_f32 v6, v0, v6
	v_lshlrev_b32_e32 v0, 16, v17
	v_add_f32_e32 v7, v29, v44
	v_mul_f32_e32 v0, v7, v0
	v_and_b32_e32 v7, 0xffff0000, v17
	v_add_f32_e32 v16, v29, v45
	v_mul_f32_e32 v7, v16, v7
	v_cvt_pk_bf16_f32 v7, v0, v7
	global_store_dwordx2 v[8:9], v[6:7], off offset:128
	s_waitcnt vmcnt(7)
	v_lshlrev_b32_e32 v0, 16, v14
	v_add_f32_e32 v6, v29, v54
	v_mul_f32_e32 v0, v6, v0
	v_and_b32_e32 v6, 0xffff0000, v14
	v_add_f32_e32 v7, v29, v55
	s_waitcnt lgkmcnt(1)
	v_mfma_f32_16x16x32_bf16 v[50:53], v[50:53], v[2:5], v[58:61]
	v_mul_f32_e32 v6, v7, v6
	v_cvt_pk_bf16_f32 v6, v0, v6
	v_lshlrev_b32_e32 v0, 16, v15
	v_add_f32_e32 v7, v29, v56
	v_mul_f32_e32 v0, v7, v0
	v_and_b32_e32 v7, 0xffff0000, v15
	v_add_f32_e32 v14, v29, v57
	v_mul_f32_e32 v7, v14, v7
	v_cvt_pk_bf16_f32 v7, v0, v7
	global_store_dwordx2 v[8:9], v[6:7], off offset:160
	s_waitcnt vmcnt(7)
	v_lshlrev_b32_e32 v0, 16, v12
	v_add_f32_e32 v6, v29, v50
	v_mul_f32_e32 v0, v6, v0
	v_and_b32_e32 v6, 0xffff0000, v12
	v_add_f32_e32 v7, v29, v51
	s_waitcnt lgkmcnt(0)
	v_mfma_f32_16x16x32_bf16 v[2:5], v[62:65], v[2:5], v[30:33]
	v_mul_f32_e32 v6, v7, v6
	v_cvt_pk_bf16_f32 v6, v0, v6
	v_lshlrev_b32_e32 v0, 16, v13
	v_add_f32_e32 v7, v29, v52
	v_mul_f32_e32 v0, v7, v0
	v_and_b32_e32 v7, 0xffff0000, v13
	v_add_f32_e32 v12, v29, v53
	v_mul_f32_e32 v7, v12, v7
	v_cvt_pk_bf16_f32 v7, v0, v7
	s_waitcnt vmcnt(6)
	v_lshlrev_b32_e32 v0, 16, v10
	v_add_f32_e32 v2, v29, v2
	v_mul_f32_e32 v0, v2, v0
	v_and_b32_e32 v2, 0xffff0000, v10
	v_add_f32_e32 v3, v29, v3
	v_mul_f32_e32 v2, v3, v2
	global_store_dwordx2 v[8:9], v[6:7], off offset:192
	v_cvt_pk_bf16_f32 v2, v0, v2
	v_lshlrev_b32_e32 v0, 16, v11
	v_add_f32_e32 v3, v29, v4
	v_mul_f32_e32 v0, v3, v0
	v_and_b32_e32 v3, 0xffff0000, v11
	v_add_f32_e32 v4, v29, v5
	v_mul_f32_e32 v3, v4, v3
	v_cvt_pk_bf16_f32 v3, v0, v3
	global_store_dwordx2 v[8:9], v[2:3], off offset:224
	s_barrier
	s_mov_b64 s[4:5], 0
